# attention main tile: 8 cross-half shuffles as v_permlane32_swap instead of ds_bpermute round trips (on top of v19)
# baseline (speedup 1.0000x reference)
.LBB0_1439:
	s_andn2_b64 vcc, exec, s[10:11]
	s_cbranch_vccnz .LBB0_1432
	v_exp_f32_e64 v82, -v201
	v_and_b32_e32 v17, 64, v167
	v_xor_b32_e32 v16, 32, v167
	v_add_u32_e32 v17, 64, v17
	v_cmp_lt_i32_e32 vcc, v16, v17
	v_add_f32_e32 v17, 1.0, v82
	v_rcp_f32_e32 v86, v17
	v_cndmask_b32_e32 v83, v167, v16, vcc
	v_exp_f32_e64 v16, -v200
	v_exp_f32_e64 v17, -v198
	v_exp_f32_e64 v82, -v197
	v_lshlrev_b32_e32 v197, 2, v83
	v_add_f32_e32 v16, 1.0, v16
	v_rcp_f32_e32 v158, v16
	v_add_f32_e32 v16, 1.0, v17
	v_rcp_f32_e32 v17, v16
	v_add_f32_e32 v16, 1.0, v82
	v_rcp_f32_e32 v16, v16
	v_sub_f32_e32 v88, 1.0, v158
	v_sub_f32_e32 v87, 1.0, v86
	v_exp_f32_e64 v2, -v2
	v_pk_add_f32 v[84:85], v[16:17], 1.0 op_sel_hi:[1,0] neg_lo:[1,0] neg_hi:[1,0]
	v_add_f32_e32 v2, 1.0, v2
	v_pk_mul_f32 v[82:83], v[84:85], v[84:85] op_sel:[0,1] op_sel_hi:[1,0]
	v_mul_f32_e32 v84, v17, v84
	v_mul_f32_e32 v85, v88, v82
	v_mul_f32_e32 v91, v87, v85
	v_mov_b32_e32 v94, v91
	s_nop 1
	v_permlane32_swap_b32_e32 v91, v94
	v_mul_f32_e32 v86, v86, v85
	v_exp_f32_e64 v85, -v196
	s_waitcnt lgkmcnt(0)
	v_cndmask_b32_e64 v83, 1.0, v94, s[8:9]
	v_pk_mul_f32 v[88:89], v[158:159], v[82:83]
	v_exp_f32_e64 v82, -v195
	v_add_f32_e32 v83, 1.0, v85
	v_rcp_f32_e32 v98, v83
	v_exp_f32_e64 v83, -v194
	v_exp_f32_e64 v85, -v193
	v_add_f32_e32 v82, 1.0, v82
	v_rcp_f32_e32 v90, v82
	v_add_f32_e32 v82, 1.0, v83
	v_rcp_f32_e32 v93, v82
	v_add_f32_e32 v82, 1.0, v85
	v_rcp_f32_e32 v92, v82
	v_mul_f32_e32 v83, v91, v94
	v_sub_f32_e32 v91, 1.0, v90
	v_sub_f32_e32 v85, 1.0, v98
	v_pk_add_f32 v[94:95], v[92:93], 1.0 op_sel_hi:[1,0] neg_lo:[1,0] neg_hi:[1,0]
	v_mov_b32_e32 v87, v88
	v_mov_b32_e32 v158, v94
	v_mov_b32_e32 v82, v95
	v_pk_mul_f32 v[96:97], v[158:159], v[82:83]
	v_pk_mul_f32 v[82:83], v[86:87], v[88:89] op_sel:[0,1]
	v_mul_f32_e32 v95, v91, v96
	v_mul_f32_e32 v100, v85, v95
	v_mov_b32_e32 v101, v100
	s_nop 1
	v_permlane32_swap_b32_e32 v100, v101
	v_mov_b32_e32 v85, v16
	v_pk_mul_f32 v[16:17], v[84:85], v[88:89] op_sel:[0,1]
	v_exp_f32_e64 v88, -v192
	v_exp_f32_e64 v89, -v191
	s_waitcnt lgkmcnt(0)
	v_cndmask_b32_e64 v91, 1.0, v101, s[8:9]
	v_pk_mul_f32 v[86:87], v[90:91], v[96:97]
	v_add_f32_e32 v88, 1.0, v88
	v_rcp_f32_e32 v102, v88
	v_exp_f32_e64 v90, -v190
	v_add_f32_e32 v88, 1.0, v89
	v_exp_f32_e64 v89, -v189
	v_mul_f32_e32 v84, v98, v95
	v_add_f32_e32 v90, 1.0, v90
	v_rcp_f32_e32 v99, v90
	v_add_f32_e32 v89, 1.0, v89
	v_rcp_f32_e32 v98, v89
	v_rcp_f32_e32 v88, v88
	v_mul_f32_e32 v91, v100, v101
	v_sub_f32_e32 v89, 1.0, v102
	v_pk_add_f32 v[100:101], v[98:99], 1.0 op_sel_hi:[1,0] neg_lo:[1,0] neg_hi:[1,0]
	v_sub_f32_e32 v95, 1.0, v88
	v_mov_b32_e32 v96, v100
	v_mov_b32_e32 v90, v101
	v_pk_mul_f32 v[90:91], v[96:97], v[90:91]
	v_mov_b32_e32 v85, v86
	v_mul_f32_e32 v96, v95, v90
	v_mul_f32_e32 v101, v89, v96
	v_mov_b32_e32 v103, v101
	s_nop 1
	v_permlane32_swap_b32_e32 v101, v103
	v_mul_f32_e32 v94, v93, v94
	v_mov_b32_e32 v95, v92
	v_pk_mul_f32 v[84:85], v[84:85], v[86:87] op_sel:[0,1]
	v_pk_mul_f32 v[86:87], v[94:95], v[86:87] op_sel:[0,1]
	s_waitcnt lgkmcnt(0)
	v_cndmask_b32_e64 v89, 1.0, v103, s[8:9]
	v_exp_f32_e64 v94, -v188
	v_pk_mul_f32 v[88:89], v[88:89], v[90:91]
	v_exp_f32_e64 v90, -v187
	v_exp_f32_e64 v95, -v186
	v_mul_f32_e32 v92, v102, v96
	v_exp_f32_e64 v96, -v185
	v_add_f32_e32 v94, 1.0, v94
	v_add_f32_e32 v90, 1.0, v90
	v_rcp_f32_e32 v106, v94
	v_rcp_f32_e32 v94, v90
	v_add_f32_e32 v90, 1.0, v95
	v_rcp_f32_e32 v97, v90
	v_add_f32_e32 v90, 1.0, v96
	v_rcp_f32_e32 v96, v90
	v_mov_b32_e32 v93, v88
	v_mul_f32_e32 v103, v101, v103
	v_sub_f32_e32 v101, 1.0, v94
	v_pk_add_f32 v[104:105], v[96:97], 1.0 op_sel_hi:[1,0] neg_lo:[1,0] neg_hi:[1,0]
	v_sub_f32_e32 v95, 1.0, v106
	v_mov_b32_e32 v90, v104
	v_mov_b32_e32 v102, v105
	v_pk_mul_f32 v[102:103], v[90:91], v[102:103]
	v_pk_mul_f32 v[90:91], v[92:93], v[88:89] op_sel:[0,1]
	v_mov_b32_e32 v93, v98
	v_exp_f32_e64 v98, -v184
	v_mul_f32_e32 v92, v99, v100
	v_exp_f32_e64 v99, -v183
	v_exp_f32_e64 v100, -v181
	v_add_f32_e32 v98, 1.0, v98
	v_rcp_f32_e32 v110, v98
	v_add_f32_e32 v98, 1.0, v99
	v_exp_f32_e64 v99, -v180
	v_mul_f32_e32 v101, v101, v102
	v_mul_f32_e32 v105, v95, v101
	v_mov_b32_e32 v107, v105
	s_nop 1
	v_permlane32_swap_b32_e32 v105, v107
	v_add_f32_e32 v100, 1.0, v100
	v_add_f32_e32 v99, 1.0, v99
	v_pk_mul_f32 v[88:89], v[92:93], v[88:89] op_sel:[0,1]
	v_mul_f32_e32 v92, v106, v101
	v_rcp_f32_e32 v101, v100
	v_rcp_f32_e32 v100, v99
	v_rcp_f32_e32 v98, v98
	s_waitcnt lgkmcnt(0)
	v_cndmask_b32_e64 v95, 1.0, v107, s[8:9]
	v_pk_mul_f32 v[94:95], v[94:95], v[102:103]
	v_pk_add_f32 v[108:109], v[100:101], 1.0 op_sel_hi:[1,0] neg_lo:[1,0] neg_hi:[1,0]
	v_mul_f32_e32 v107, v105, v107
	v_mov_b32_e32 v102, v108
	v_mov_b32_e32 v106, v109
	v_sub_f32_e32 v105, 1.0, v98
	v_pk_mul_f32 v[102:103], v[102:103], v[106:107]
	v_sub_f32_e32 v99, 1.0, v110
	v_mul_f32_e32 v106, v105, v102
	v_mul_f32_e32 v107, v99, v106
	v_mov_b32_e32 v109, v107
	s_nop 1
	v_permlane32_swap_b32_e32 v107, v109
	v_mov_b32_e32 v105, v96
	v_mul_f32_e32 v96, v110, v106
	v_exp_f32_e64 v106, -v179
	v_mov_b32_e32 v93, v94
	v_mul_f32_e32 v104, v97, v104
	s_waitcnt lgkmcnt(0)
	v_cndmask_b32_e64 v99, 1.0, v109, s[8:9]
	v_pk_mul_f32 v[92:93], v[92:93], v[94:95] op_sel:[0,1]
	v_pk_mul_f32 v[94:95], v[104:105], v[94:95] op_sel:[0,1]
	v_pk_mul_f32 v[104:105], v[98:99], v[102:103]
	v_exp_f32_e64 v98, -v178
	v_add_f32_e32 v99, 1.0, v106
	v_rcp_f32_e32 v178, v99
	v_exp_f32_e64 v99, -v177
	v_exp_f32_e64 v102, -v176
	v_add_f32_e32 v98, 1.0, v98
	v_rcp_f32_e32 v106, v98
	v_add_f32_e32 v98, 1.0, v99
	v_rcp_f32_e32 v111, v98
	v_add_f32_e32 v98, 1.0, v102
	v_rcp_f32_e32 v110, v98
	v_mul_f32_e32 v99, v107, v109
	v_sub_f32_e32 v109, 1.0, v106
	v_sub_f32_e32 v107, 1.0, v178
	v_pk_add_f32 v[158:159], v[110:111], 1.0 op_sel_hi:[1,0] neg_lo:[1,0] neg_hi:[1,0]
	v_mov_b32_e32 v97, v104
	v_mov_b32_e32 v102, v158
	v_mov_b32_e32 v98, v159
	v_pk_mul_f32 v[102:103], v[102:103], v[98:99]
	v_pk_mul_f32 v[98:99], v[96:97], v[104:105] op_sel:[0,1]
	v_mul_f32_e32 v109, v109, v102
	v_mul_f32_e32 v159, v107, v109
	v_mov_b32_e32 v176, v159
	s_nop 1
	v_permlane32_swap_b32_e32 v159, v176
	v_mul_f32_e32 v96, v101, v108
	v_mov_b32_e32 v97, v100
	v_pk_mul_f32 v[96:97], v[96:97], v[104:105] op_sel:[0,1]
	v_exp_f32_e64 v108, -v173
	s_waitcnt lgkmcnt(0)
	v_cndmask_b32_e64 v107, 1.0, v176, s[8:9]
	v_pk_mul_f32 v[104:105], v[106:107], v[102:103]
	v_exp_f32_e64 v107, -v174
	v_mul_f32_e32 v100, v178, v109
	v_exp_f32_e64 v102, -v175
	v_mul_f32_e32 v109, v159, v176
	v_add_f32_e32 v107, 1.0, v107
	v_rcp_f32_e32 v159, v107
	v_add_f32_e32 v107, 1.0, v108
	v_mul_f32_e32 v106, v111, v158
	v_exp_f32_e64 v111, -v172
	v_rcp_f32_e32 v158, v107
	v_add_f32_e32 v102, 1.0, v102
	v_rcp_f32_e32 v172, v102
	v_add_f32_e32 v102, 1.0, v111
	v_pk_add_f32 v[176:177], v[158:159], 1.0 op_sel_hi:[1,0] neg_lo:[1,0] neg_hi:[1,0]
	v_rcp_f32_e32 v174, v102
	v_mov_b32_e32 v102, v176
	v_mov_b32_e32 v108, v177
	v_pk_mul_f32 v[108:109], v[102:103], v[108:109]
	v_exp_f32_e64 v103, -v113
	v_exp_f32_e64 v107, -v112
	v_exp_f32_e64 v102, -v171
	v_rcp_f32_e32 v111, v2
	v_add_f32_e32 v103, 1.0, v103
	v_add_f32_e32 v107, 1.0, v107
	v_rcp_f32_e32 v175, v107
	v_rcp_f32_e32 v113, v103
	v_add_f32_e32 v102, 1.0, v102
	v_rcp_f32_e32 v112, v102
	v_sub_f32_e32 v179, 1.0, v111
	v_pk_add_f32 v[102:103], v[174:175], 1.0 op_sel_hi:[1,0] neg_lo:[1,0] neg_hi:[1,0]
	v_mov_b32_e32 v173, v113
	v_mov_b32_e32 v178, v108
	v_pk_add_f32 v[180:181], v[172:173], 1.0 op_sel_hi:[1,0] neg_lo:[1,0] neg_hi:[1,0]
	v_pk_mul_f32 v[184:185], v[102:103], v[178:179]
	v_mov_b32_e32 v101, v104
	v_pk_mul_f32 v[180:181], v[180:181], v[184:185]
	v_mov_b32_e32 v186, v180
	s_nop 1
	v_permlane32_swap_b32_e32 v180, v186
	v_mov_b32_e32 v107, v110
	v_sub_f32_e32 v187, 1.0, v112
	v_pk_mul_f32 v[100:101], v[100:101], v[104:105] op_sel:[0,1]
	v_pk_mul_f32 v[102:103], v[106:107], v[104:105] op_sel:[0,1]
	s_waitcnt lgkmcnt(0)
	v_cndmask_b32_e64 v105, 1.0, v186, s[8:9]
	v_pk_mul_f32 v[186:187], v[180:181], v[186:187]
	v_mul_f32_e32 v106, v159, v176
	v_mov_b32_e32 v159, v187
	s_nop 1
	v_permlane32_swap_b32_e32 v187, v159
	v_mov_b32_e32 v104, v174
	v_mov_b32_e32 v107, v158
	v_mov_b32_e32 v158, v109
	v_mul_f32_e32 v172, v172, v184
	v_pk_mul_f32 v[176:177], v[104:105], v[108:109]
	s_waitcnt lgkmcnt(0)
	v_cndmask_b32_e64 v2, 1.0, v159, s[8:9]
	v_pk_mul_f32 v[158:159], v[158:159], v[186:187]
	v_mov_b32_e32 v184, v181
	v_mov_b32_e32 v173, v176
	v_mul_f32_e32 v2, v158, v2
	v_pk_mul_f32 v[108:109], v[112:113], v[184:185]
	v_mul_f32_e32 v110, v175, v179
	v_pk_mul_f32 v[104:105], v[172:173], v[176:177] op_sel:[0,1]
	v_pk_mul_f32 v[106:107], v[106:107], v[176:177] op_sel:[0,1]
	v_pk_mul_f32 v[108:109], v[108:109], v[2:3] op_sel_hi:[1,0]
	v_pk_mul_f32 v[110:111], v[110:111], v[2:3] op_sel_hi:[1,0]
	v_mul_f32_e32 v158, v158, v159
	s_branch .LBB0_1432
